# P0 rmsnorm rows: norm_g hoisted out of the row loop into registers, per-chunk vmcnt(0) waits removed (on top of transposes MLP + attention changes)
# baseline (speedup 1.0000x reference)
; DI unsigned pk2(float lo, float hi) { f32x2_t v = {lo, hi}; bf16x2_t b = __builtin_convertvector(v, bf16x2_t); return __builtin_bit_cast(unsigned, b); }
; DI void p0_rmsnorm_rows(const float* x, const float* g, bf16_t* h, int gw, int nw, int lane) {
;     for (int row = gw; row < MTOK; row += nw) {
;         const f32x4* xr = (const f32x4*)(x + (size_t)row * DM) + lane;
;         f32x4 v[8]; float s = 0.f;
; #pragma unroll
;         for (int j = 0; j < 8; ++j) { v[j] = __builtin_nontemporal_load(xr + 64 * j); s += (v[j].x * v[j].x + v[j].y * v[j].y) + (v[j].z * v[j].z + v[j].w * v[j].w); }
;         s = wave_sum(s);
;         const float rstd = __builtin_amdgcn_rsqf(s * (1.0f / DM) + EPS);
;         u32x2* o8 = (u32x2*)(h + (size_t)row * DM) + lane;
; #pragma unroll
;         for (int j = 0; j < 8; ++j) {
;             const f32x4 gg = ((const f32x4*)g)[lane + 64 * j];
;             u32x2 o; o.x = pk2(v[j].x * rstd * gg.x, v[j].y * rstd * gg.y); o.y = pk2(v[j].z * rstd * gg.z, v[j].w * rstd * gg.w);
;             o8[64 * j] = o;
;         }
;     }
; }
; __global__ __launch_bounds__(NTHREADS, 2) void hymba_mega(Params p) {
;     ...
;     const int tid = threadIdx.x, lane = tid & 63, wid = __builtin_amdgcn_readfirstlane(tid >> 6);
;     const int bid = blockIdx.x, G = gridDim.x;
;     const int gw = bid * 8 + wid, nw = G * 8;
_Z10hymba_mega6Params:
	s_load_dwordx2 s[44:45], s[0:1], 0x0
	s_load_dwordx2 s[42:43], s[0:1], 0x80
	s_load_dwordx4 s[36:39], s[0:1], 0x70
	s_load_dwordx8 s[24:31], s[0:1], 0x50
	s_load_dword s3, s[0:1], 0x88
	v_and_b32_e32 v1, 0x3ff, v0
	s_add_u32 s48, s0, 0x88
	v_readfirstlane_b32 s41, v1
	s_addc_u32 s49, s1, 0
	s_lshr_b32 s53, s41, 6
	s_lshl_b32 s4, s2, 3
	s_add_i32 s40, s53, s4
	s_waitcnt lgkmcnt(0)
	s_lshl_b32 s34, s3, 3
	s_cmp_lt_i32 s40, 0x8000
	v_and_b32_e32 v16, 63, v0
	s_cselect_b64 s[46:47], -1, 0
	s_cmpk_gt_i32 s40, 0x7fff
	v_mbcnt_lo_u32_b32 v145, -1, 0
	s_cbranch_scc1 .LBB0_3
	v_mbcnt_hi_u32_b32 v2, -1, v145
	v_and_b32_e32 v3, 64, v2
	v_add_u32_e32 v3, 64, v3
	v_xor_b32_e32 v4, 1, v2
	v_cmp_lt_i32_e32 vcc, v4, v3
	s_load_dwordx2 s[6:7], s[0:1], 0x8
	v_lshlrev_b32_e32 v14, 4, v16
	v_cndmask_b32_e32 v4, v2, v4, vcc
	v_lshlrev_b32_e32 v17, 2, v4
	v_xor_b32_e32 v4, 2, v2
	v_cmp_lt_i32_e32 vcc, v4, v3
	v_mov_b32_e32 v15, 0
	s_mov_b64 s[8:9], 0x1400
	v_cndmask_b32_e32 v4, v2, v4, vcc
	v_lshlrev_b32_e32 v18, 2, v4
	v_xor_b32_e32 v4, 4, v2
	v_cmp_lt_i32_e32 vcc, v4, v3
	s_ashr_i32 s5, s4, 31
	v_mov_b32_e32 v23, 0x358637bd
	v_cndmask_b32_e32 v4, v2, v4, vcc
	v_lshlrev_b32_e32 v19, 2, v4
	v_xor_b32_e32 v4, 8, v2
	v_cmp_lt_i32_e32 vcc, v4, v3
	s_nop 1
	v_cndmask_b32_e32 v4, v2, v4, vcc
	v_lshlrev_b32_e32 v20, 2, v4
	v_xor_b32_e32 v4, 16, v2
	v_cmp_lt_i32_e32 vcc, v4, v3
	s_nop 1
	v_cndmask_b32_e32 v4, v2, v4, vcc
	v_lshlrev_b32_e32 v21, 2, v4
	v_xor_b32_e32 v4, 32, v2
	v_cmp_lt_i32_e32 vcc, v4, v3
	s_nop 1
	v_cndmask_b32_e32 v2, v2, v4, vcc
	v_lshlrev_b32_e32 v22, 2, v2
	s_waitcnt lgkmcnt(0)
	v_lshl_add_u64 v[2:3], s[6:7], 0, v[14:15]
	v_lshl_add_u64 v[6:7], v[2:3], 0, s[8:9]
	s_mov_b64 s[8:9], 0x1800
	v_lshl_add_u64 v[8:9], v[2:3], 0, s[8:9]
	s_mov_b64 s[8:9], 0x1c00
	v_lshl_add_u64 v[10:11], v[2:3], 0, s[8:9]
	s_add_u32 s8, s53, s4
	s_addc_u32 s9, 0, s5
	s_lshl_b64 s[4:5], s[8:9], 13
	s_add_u32 s4, s44, s4
	s_addc_u32 s5, s45, s5
	s_mov_b64 s[6:7], 0x1000
	v_lshl_add_u64 v[12:13], s[4:5], 0, v[14:15]
	s_ashr_i32 s35, s34, 31
	v_lshl_add_u64 v[4:5], v[2:3], 0, s[6:7]
	v_lshl_add_u64 v[12:13], v[12:13], 0, s[6:7]
	s_lshl_b64 s[4:5], s[34:35], 13
	s_lshl_b64 s[6:7], s[8:9], 12
	s_add_u32 s6, s42, s6
	v_lshlrev_b32_e32 v14, 3, v16
	s_addc_u32 s7, s43, s7
	v_lshl_add_u64 v[14:15], s[6:7], 0, v[14:15]
	s_mov_b64 s[6:7], 0x800
	v_lshl_add_u64 v[14:15], v[14:15], 0, s[6:7]
	s_lshl_b64 s[6:7], s[34:35], 12
	s_mov_b32 s8, s40
	global_load_dwordx4 v[96:99], v[2:3], off
	global_load_dwordx4 v[100:103], v[2:3], off offset:1024
	global_load_dwordx4 v[104:107], v[2:3], off offset:2048
	global_load_dwordx4 v[108:111], v[2:3], off offset:3072
	global_load_dwordx4 v[112:115], v[4:5], off
	global_load_dwordx4 v[116:119], v[6:7], off
	global_load_dwordx4 v[120:123], v[8:9], off
	global_load_dwordx4 v[124:127], v[10:11], off
	s_waitcnt vmcnt(0)
; DI unsigned pk2(float lo, float hi) { f32x2_t v = {lo, hi}; bf16x2_t b = __builtin_convertvector(v, bf16x2_t); return __builtin_bit_cast(unsigned, b); }
; DI void p0_rmsnorm_rows(const float* x, const float* g, bf16_t* h, int gw, int nw, int lane) {
;     for (int row = gw; row < MTOK; row += nw) {
;         const f32x4* xr = (const f32x4*)(x + (size_t)row * DM) + lane;
;         f32x4 v[8]; float s = 0.f;
; #pragma unroll
;         for (int j = 0; j < 8; ++j) { v[j] = __builtin_nontemporal_load(xr + 64 * j); s += (v[j].x * v[j].x + v[j].y * v[j].y) + (v[j].z * v[j].z + v[j].w * v[j].w); }
;         s = wave_sum(s);
;         const float rstd = __builtin_amdgcn_rsqf(s * (1.0f / DM) + EPS);
;         u32x2* o8 = (u32x2*)(h + (size_t)row * DM) + lane;
; #pragma unroll
;         for (int j = 0; j < 8; ++j) {
;             const f32x4 gg = ((const f32x4*)g)[lane + 64 * j];
;             u32x2 o; o.x = pk2(v[j].x * rstd * gg.x, v[j].y * rstd * gg.y); o.y = pk2(v[j].z * rstd * gg.z, v[j].w * rstd * gg.w);
;             o8[64 * j] = o;
;         }
;     }
.LBB0_2:
	global_load_dwordx4 v[24:27], v[12:13], off offset:-4096 nt
	global_load_dwordx4 v[28:31], v[12:13], off offset:-3072 nt
	global_load_dwordx4 v[32:35], v[12:13], off offset:-2048 nt
	global_load_dwordx4 v[36:39], v[12:13], off offset:1024 nt
	global_load_dwordx4 v[40:43], v[12:13], off nt
	global_load_dwordx4 v[44:47], v[12:13], off offset:-1024 nt
	global_load_dwordx4 v[48:51], v[12:13], off offset:2048 nt
	global_load_dwordx4 v[52:55], v[12:13], off offset:3072 nt
	s_add_i32 s8, s8, s34
	v_lshl_add_u64 v[12:13], v[12:13], 0, s[4:5]
	s_cmp_lt_i32 s8, 0x8000
	s_waitcnt vmcnt(7)
	v_mov_b32_e32 v62, v25
	s_waitcnt vmcnt(6)
	v_mov_b32_e32 v63, v29
	s_waitcnt vmcnt(5)
	v_pk_mul_f32 v[64:65], v[34:35], v[34:35]
	v_pk_mul_f32 v[66:67], v[32:33], v[32:33]
	s_waitcnt vmcnt(4)
	v_pk_mul_f32 v[68:69], v[38:39], v[38:39]
	v_pk_mul_f32 v[70:71], v[36:37], v[36:37]
	v_mov_b32_e32 v74, v27
	v_mov_b32_e32 v75, v31
	v_mov_b32_e32 v60, v24
	v_mov_b32_e32 v61, v28
	v_mov_b32_e32 v72, v26
	v_mov_b32_e32 v73, v30
	v_pk_mov_b32 v[84:85], v[66:67], v[64:65] op_sel:[1,0]
	v_mov_b32_e32 v67, v65
	v_pk_mov_b32 v[64:65], v[70:71], v[68:69] op_sel:[1,0]
	v_mov_b32_e32 v71, v69
	v_pk_mul_f32 v[62:63], v[62:63], v[62:63]
	v_pk_mul_f32 v[68:69], v[74:75], v[74:75]
	v_pk_fma_f32 v[60:61], v[60:61], v[60:61], v[62:63]
	v_pk_fma_f32 v[62:63], v[72:73], v[72:73], v[68:69]
	s_waitcnt vmcnt(2)
	v_mul_f32_e32 v76, v45, v45
	v_mul_f32_e32 v78, v47, v47
	v_pk_add_f32 v[66:67], v[84:85], v[66:67]
	v_pk_add_f32 v[60:61], v[60:61], v[62:63]
	v_mul_f32_e32 v83, v42, v42
	v_mul_f32_e32 v86, v43, v43
	v_mul_f32_e32 v89, v41, v41
	v_mul_f32_e32 v90, v40, v40
	v_pk_fma_f32 v[74:75], v[44:45], v[44:45], v[76:77] op_sel_hi:[1,1,0]
	v_pk_fma_f32 v[76:77], v[46:47], v[46:47], v[78:79] op_sel_hi:[1,1,0]
	v_pk_add_f32 v[66:67], v[66:67], v[66:67] op_sel:[0,1] op_sel_hi:[1,0]
	v_pk_add_f32 v[60:61], v[60:61], v[60:61] op_sel:[0,1] op_sel_hi:[1,0]
	v_mov_b32_e32 v75, v83
	v_mov_b32_e32 v77, v86
	v_mov_b32_e32 v67, v89
	v_mov_b32_e32 v61, v90
	v_pk_add_f32 v[62:63], v[74:75], v[76:77]
	v_pk_add_f32 v[60:61], v[60:61], v[66:67]
	s_waitcnt vmcnt(1)
	v_mul_f32_e32 v80, v49, v49
	v_mul_f32_e32 v82, v51, v51
	v_pk_add_f32 v[64:65], v[64:65], v[70:71]
	v_pk_add_f32 v[60:61], v[60:61], v[62:63]
	s_waitcnt vmcnt(0)
	v_mul_f32_e32 v87, v54, v54
	v_mul_f32_e32 v88, v55, v55
	v_mul_f32_e32 v91, v53, v53
	v_mul_f32_e32 v92, v52, v52
	v_pk_fma_f32 v[78:79], v[48:49], v[48:49], v[80:81] op_sel_hi:[1,1,0]
	v_pk_fma_f32 v[80:81], v[50:51], v[50:51], v[82:83] op_sel_hi:[1,1,0]
	v_pk_add_f32 v[64:65], v[64:65], v[64:65] op_sel:[0,1] op_sel_hi:[1,0]
	v_pk_add_f32 v[60:61], v[60:61], v[60:61] op_sel:[0,1] op_sel_hi:[1,0]
	v_mov_b32_e32 v79, v87
	v_mov_b32_e32 v81, v88
	v_mov_b32_e32 v65, v91
	v_mov_b32_e32 v61, v92
	v_pk_add_f32 v[68:69], v[78:79], v[80:81]
	v_pk_add_f32 v[60:61], v[60:61], v[64:65]
	s_nop 0
	v_pk_add_f32 v[60:61], v[60:61], v[68:69]
	s_nop 0
	v_add_f32_e32 v60, v60, v61
	ds_bpermute_b32 v61, v17, v60
	s_waitcnt lgkmcnt(0)
	v_add_f32_e32 v60, v60, v61
	ds_bpermute_b32 v61, v18, v60
	s_waitcnt lgkmcnt(0)
	v_add_f32_e32 v60, v60, v61
	ds_bpermute_b32 v61, v19, v60
	s_waitcnt lgkmcnt(0)
	v_add_f32_e32 v60, v60, v61
	ds_bpermute_b32 v61, v20, v60
	s_waitcnt lgkmcnt(0)
	v_add_f32_e32 v60, v60, v61
	ds_bpermute_b32 v61, v21, v60
	s_waitcnt lgkmcnt(0)
	v_add_f32_e32 v60, v60, v61
	ds_bpermute_b32 v61, v22, v60
	s_waitcnt lgkmcnt(0)
	v_add_f32_e32 v60, v60, v61
	v_fmamk_f32 v60, v60, 0x3a000000, v23
	v_rsq_f32_e32 v60, v60
	s_nop 0
	v_pk_mul_f32 v[24:25], v[24:25], v[60:61] op_sel_hi:[1,0]
	v_pk_mul_f32 v[26:27], v[26:27], v[60:61] op_sel_hi:[1,0]
	v_pk_mul_f32 v[24:25], v[96:97], v[24:25]
	v_pk_mul_f32 v[26:27], v[98:99], v[26:27]
	v_cvt_pk_bf16_f32 v24, v24, v25
	v_cvt_pk_bf16_f32 v25, v26, v27
	global_store_dwordx2 v[14:15], v[24:25], off offset:-2048
	v_pk_mul_f32 v[28:29], v[28:29], v[60:61] op_sel_hi:[1,0]
	v_pk_mul_f32 v[30:31], v[30:31], v[60:61] op_sel_hi:[1,0]
	v_pk_mul_f32 v[24:25], v[100:101], v[28:29]
	v_pk_mul_f32 v[26:27], v[102:103], v[30:31]
	v_cvt_pk_bf16_f32 v24, v24, v25
	v_cvt_pk_bf16_f32 v25, v26, v27
	global_store_dwordx2 v[14:15], v[24:25], off offset:-1536
	v_pk_mul_f32 v[28:29], v[32:33], v[60:61] op_sel_hi:[1,0]
	v_pk_mul_f32 v[30:31], v[34:35], v[60:61] op_sel_hi:[1,0]
	v_pk_mul_f32 v[24:25], v[104:105], v[28:29]
	v_pk_mul_f32 v[26:27], v[106:107], v[30:31]
	v_cvt_pk_bf16_f32 v24, v24, v25
	v_cvt_pk_bf16_f32 v25, v26, v27
	global_store_dwordx2 v[14:15], v[24:25], off offset:-1024
	v_pk_mul_f32 v[28:29], v[44:45], v[60:61] op_sel_hi:[1,0]
	v_pk_mul_f32 v[30:31], v[46:47], v[60:61] op_sel_hi:[1,0]
	v_pk_mul_f32 v[24:25], v[108:109], v[28:29]
	v_pk_mul_f32 v[26:27], v[110:111], v[30:31]
	v_cvt_pk_bf16_f32 v24, v24, v25
	v_cvt_pk_bf16_f32 v25, v26, v27
	global_store_dwordx2 v[14:15], v[24:25], off offset:-512
	v_pk_mul_f32 v[28:29], v[40:41], v[60:61] op_sel_hi:[1,0]
	v_pk_mul_f32 v[30:31], v[42:43], v[60:61] op_sel_hi:[1,0]
	v_pk_mul_f32 v[24:25], v[28:29], v[112:113]
	v_pk_mul_f32 v[26:27], v[30:31], v[114:115]
	v_cvt_pk_bf16_f32 v24, v24, v25
	v_cvt_pk_bf16_f32 v25, v26, v27
	global_store_dwordx2 v[14:15], v[24:25], off
	v_pk_mul_f32 v[28:29], v[36:37], v[60:61] op_sel_hi:[1,0]
	v_pk_mul_f32 v[30:31], v[38:39], v[60:61] op_sel_hi:[1,0]
	v_pk_mul_f32 v[24:25], v[28:29], v[116:117]
	v_pk_mul_f32 v[26:27], v[30:31], v[118:119]
	v_cvt_pk_bf16_f32 v24, v24, v25
	v_cvt_pk_bf16_f32 v25, v26, v27
	global_store_dwordx2 v[14:15], v[24:25], off offset:512
	v_pk_mul_f32 v[28:29], v[48:49], v[60:61] op_sel_hi:[1,0]
	v_pk_mul_f32 v[30:31], v[50:51], v[60:61] op_sel_hi:[1,0]
	v_pk_mul_f32 v[24:25], v[28:29], v[120:121]
	v_pk_mul_f32 v[26:27], v[30:31], v[122:123]
	v_cvt_pk_bf16_f32 v24, v24, v25
	v_cvt_pk_bf16_f32 v25, v26, v27
	global_store_dwordx2 v[14:15], v[24:25], off offset:1024
	v_pk_mul_f32 v[28:29], v[52:53], v[60:61] op_sel_hi:[1,0]
	v_pk_mul_f32 v[30:31], v[54:55], v[60:61] op_sel_hi:[1,0]
	v_pk_mul_f32 v[24:25], v[28:29], v[124:125]
	v_pk_mul_f32 v[26:27], v[30:31], v[126:127]
	v_cvt_pk_bf16_f32 v24, v24, v25
	v_cvt_pk_bf16_f32 v25, v26, v27
	global_store_dwordx2 v[14:15], v[24:25], off offset:1536
	v_lshl_add_u64 v[14:15], v[14:15], 0, s[6:7]
	s_cbranch_scc1 .LBB0_2
